# v33: v29 without the second (redundant) s_waitcnt lgkmcnt(0) between the segment barrier and the first MFMA in the three GEMM loops
# speedup vs baseline: 1.0086x; 1.0003x over previous
.LBB0_155:
	s_ashr_i32 s23, s22, 31
	s_lshl_b64 s[8:9], s[22:23], 19
	s_add_u32 s24, s30, s8
	s_addc_u32 s25, s31, s9
	s_and_b64 s[8:9], s[4:5], exec
	s_cselect_b32 s3, s25, s1
	s_cselect_b32 s23, s24, s0
	s_ashr_i32 s21, s20, 31
	s_lshl_b64 s[8:9], s[20:21], 19
	s_add_u32 s26, s34, s8
	s_addc_u32 s27, s35, s9
	s_and_b64 s[8:9], s[4:5], exec
	s_cselect_b32 s21, s27, s7
	s_cselect_b32 s28, s26, s6
	s_add_u32 s0, s0, 0x40080
	s_addc_u32 s1, s1, 0
	s_add_u32 s29, s6, 0x100
	s_addc_u32 s42, s7, 0
	s_mov_b32 s49, -2
	s_add_u32 s6, s0, 0xfffc0080
	s_addc_u32 s7, s1, -1
	s_add_i32 s50, 16, 0x10000
	s_cmp_eq_u32 s49, 12
	s_cselect_b32 s9, s3, s7
	s_cselect_b32 s8, s23, s6
	v_add_u32_e32 v151, s50, v176
	s_cselect_b32 s7, s21, s42
	s_cselect_b32 s6, s28, s29
	s_add_i32 s52, 16, 0x14000
	ds_read_b128 v[132:135], v151
	ds_read_b128 v[152:155], v151 offset:1024
	ds_read_b128 v[156:159], v151 offset:2048
	ds_read_b128 v[160:163], v151 offset:3072
	v_add_u32_e32 v151, s52, v176
	ds_read_b128 v[164:167], v151
	ds_read_b128 v[168:171], v151 offset:1024
	ds_read_b128 v[172:175], v151 offset:2048
	ds_read_b128 v[180:183], v151 offset:3072
	v_lshl_add_u64 v[216:217], s[0:1], 0, v[146:147]
	s_add_i32 m0, s37, 0xc000
	ds_read_b128 v[184:187], v178
	ds_read_b128 v[188:191], v178 offset:1024
	ds_read_b128 v[192:195], v178 offset:2048
	ds_read_b128 v[196:199], v178 offset:3072
	ds_read_b128 v[200:203], v178 offset:4096
	ds_read_b128 v[204:207], v178 offset:5120
	ds_read_b128 v[208:211], v178 offset:6144
	ds_read_b128 v[212:215], v178 offset:7168
	global_load_lds_dwordx4 v[216:217], off
	v_lshl_add_u64 v[216:217], s[0:1], 0, v[148:149]
	s_add_i32 m0, s37, 0xe000
	s_nop 0
	global_load_lds_dwordx4 v[216:217], off
	s_waitcnt vmcnt(8)
	s_waitcnt lgkmcnt(0)
	s_barrier
	s_setprio 1
	v_mfma_f32_16x16x32_bf16 v[128:131], v[132:135], v[184:187], 0
	v_mfma_f32_16x16x32_bf16 v[124:127], v[156:159], v[184:187], 0
	v_mfma_f32_16x16x32_bf16 v[112:115], v[132:135], v[192:195], 0
	v_mfma_f32_16x16x32_bf16 v[108:111], v[156:159], v[192:195], 0
	v_mfma_f32_16x16x32_bf16 v[96:99], v[132:135], v[200:203], 0
	v_mfma_f32_16x16x32_bf16 v[92:95], v[156:159], v[200:203], 0
	v_mfma_f32_16x16x32_bf16 v[80:83], v[132:135], v[208:211], 0
	v_mfma_f32_16x16x32_bf16 v[76:79], v[156:159], v[208:211], 0
	v_mfma_f32_16x16x32_bf16 v[128:131], v[152:155], v[188:191], v[128:131]
	v_mfma_f32_16x16x32_bf16 v[124:127], v[160:163], v[188:191], v[124:127]
	v_mfma_f32_16x16x32_bf16 v[112:115], v[152:155], v[196:199], v[112:115]
	v_mfma_f32_16x16x32_bf16 v[108:111], v[160:163], v[196:199], v[108:111]
	v_mfma_f32_16x16x32_bf16 v[96:99], v[152:155], v[204:207], v[96:99]
	v_mfma_f32_16x16x32_bf16 v[92:95], v[160:163], v[204:207], v[92:95]
	v_mfma_f32_16x16x32_bf16 v[80:83], v[152:155], v[212:215], v[80:83]
	v_mfma_f32_16x16x32_bf16 v[76:79], v[160:163], v[212:215], v[76:79]
	s_setprio 0
	s_setprio 1
	v_mfma_f32_16x16x32_bf16 v[120:123], v[164:167], v[184:187], 0
	v_mfma_f32_16x16x32_bf16 v[116:119], v[172:175], v[184:187], 0
	v_mfma_f32_16x16x32_bf16 v[104:107], v[164:167], v[192:195], 0
	v_mfma_f32_16x16x32_bf16 v[100:103], v[172:175], v[192:195], 0
	v_mfma_f32_16x16x32_bf16 v[88:91], v[164:167], v[200:203], 0
	v_mfma_f32_16x16x32_bf16 v[84:87], v[172:175], v[200:203], 0
	v_mfma_f32_16x16x32_bf16 v[72:75], v[164:167], v[208:211], 0
	v_mfma_f32_16x16x32_bf16 v[68:71], v[172:175], v[208:211], 0
	v_mfma_f32_16x16x32_bf16 v[120:123], v[168:171], v[188:191], v[120:123]
	v_mfma_f32_16x16x32_bf16 v[116:119], v[180:183], v[188:191], v[116:119]
	v_mfma_f32_16x16x32_bf16 v[104:107], v[168:171], v[196:199], v[104:107]
	v_mfma_f32_16x16x32_bf16 v[100:103], v[180:183], v[196:199], v[100:103]
	v_mfma_f32_16x16x32_bf16 v[88:91], v[168:171], v[204:207], v[88:91]
	v_mfma_f32_16x16x32_bf16 v[84:87], v[180:183], v[204:207], v[84:87]
	v_mfma_f32_16x16x32_bf16 v[72:75], v[168:171], v[212:215], v[72:75]
	v_mfma_f32_16x16x32_bf16 v[68:71], v[180:183], v[212:215], v[68:71]
	s_setprio 0
	s_barrier
	s_add_i32 s50, s50, s36
	v_lshl_add_u64 v[216:217], s[6:7], 0, v[138:139]
	s_mov_b32 m0, s50
	ds_read_b128 v[184:187], v178 offset:16384
	ds_read_b128 v[188:191], v178 offset:17408
	ds_read_b128 v[192:195], v178 offset:18432
	ds_read_b128 v[196:199], v178 offset:19456
	ds_read_b128 v[200:203], v178 offset:20480
	ds_read_b128 v[204:207], v178 offset:21504
	ds_read_b128 v[208:211], v178 offset:22528
	ds_read_b128 v[212:215], v178 offset:23552
	global_load_lds_dwordx4 v[216:217], off
	s_add_i32 m0, s50, 0x2000
	s_add_u32 s50, s6, 0x40000
	v_lshl_add_u64 v[218:219], s[6:7], 0, v[0:1]
	s_addc_u32 s51, s7, 0
	s_add_i32 s52, s52, s36
	global_load_lds_dwordx4 v[218:219], off
	v_lshl_add_u64 v[220:221], s[50:51], 0, v[138:139]
	s_mov_b32 m0, s52
	v_lshl_add_u64 v[224:225], s[8:9], 0, v[136:137]
	global_load_lds_dwordx4 v[220:221], off
	v_lshl_add_u64 v[220:221], s[50:51], 0, v[0:1]
	s_add_i32 m0, s52, 0x2000
	s_nop 0
	global_load_lds_dwordx4 v[220:221], off
	v_lshl_add_u64 v[220:221], s[8:9], 0, v[140:141]
	s_waitcnt vmcnt(6)
	s_waitcnt lgkmcnt(0)
	s_barrier
	s_setprio 1
	v_mfma_f32_16x16x32_bf16 v[64:67], v[132:135], v[184:187], 0
	v_mfma_f32_16x16x32_bf16 v[60:63], v[156:159], v[184:187], 0
	v_mfma_f32_16x16x32_bf16 v[48:51], v[132:135], v[192:195], 0
	v_mfma_f32_16x16x32_bf16 v[44:47], v[156:159], v[192:195], 0
	v_mfma_f32_16x16x32_bf16 v[32:35], v[132:135], v[200:203], 0
	v_mfma_f32_16x16x32_bf16 v[28:31], v[156:159], v[200:203], 0
	v_mfma_f32_16x16x32_bf16 v[16:19], v[132:135], v[208:211], 0
	v_mfma_f32_16x16x32_bf16 v[12:15], v[156:159], v[208:211], 0
	v_mfma_f32_16x16x32_bf16 v[64:67], v[152:155], v[188:191], v[64:67]
	v_mfma_f32_16x16x32_bf16 v[60:63], v[160:163], v[188:191], v[60:63]
	v_mfma_f32_16x16x32_bf16 v[48:51], v[152:155], v[196:199], v[48:51]
	v_mfma_f32_16x16x32_bf16 v[44:47], v[160:163], v[196:199], v[44:47]
	v_mfma_f32_16x16x32_bf16 v[32:35], v[152:155], v[204:207], v[32:35]
	v_mfma_f32_16x16x32_bf16 v[28:31], v[160:163], v[204:207], v[28:31]
	v_mfma_f32_16x16x32_bf16 v[16:19], v[152:155], v[212:215], v[16:19]
	v_mfma_f32_16x16x32_bf16 v[12:15], v[160:163], v[212:215], v[12:15]
	s_setprio 0
	s_setprio 1
	v_mfma_f32_16x16x32_bf16 v[56:59], v[164:167], v[184:187], 0
	v_mfma_f32_16x16x32_bf16 v[52:55], v[172:175], v[184:187], 0
	v_mfma_f32_16x16x32_bf16 v[40:43], v[164:167], v[192:195], 0
	v_mfma_f32_16x16x32_bf16 v[36:39], v[172:175], v[192:195], 0
	v_mfma_f32_16x16x32_bf16 v[24:27], v[164:167], v[200:203], 0
	v_mfma_f32_16x16x32_bf16 v[20:23], v[172:175], v[200:203], 0
	v_mfma_f32_16x16x32_bf16 v[8:11], v[164:167], v[208:211], 0
	v_mfma_f32_16x16x32_bf16 v[4:7], v[172:175], v[208:211], 0
	v_mfma_f32_16x16x32_bf16 v[56:59], v[168:171], v[188:191], v[56:59]
	v_mfma_f32_16x16x32_bf16 v[52:55], v[180:183], v[188:191], v[52:55]
	v_mfma_f32_16x16x32_bf16 v[40:43], v[168:171], v[196:199], v[40:43]
	v_mfma_f32_16x16x32_bf16 v[36:39], v[180:183], v[196:199], v[36:39]
	v_mfma_f32_16x16x32_bf16 v[24:27], v[168:171], v[204:207], v[24:27]
	v_mfma_f32_16x16x32_bf16 v[20:23], v[180:183], v[204:207], v[20:23]
	v_mfma_f32_16x16x32_bf16 v[8:11], v[168:171], v[212:215], v[8:11]
	v_mfma_f32_16x16x32_bf16 v[4:7], v[180:183], v[212:215], v[4:7]
	s_setprio 0
	s_barrier
	s_branch .Lb1_ph3
.LBB0_156:
	s_add_u32 s6, s0, 0xfffc0080
	s_addc_u32 s7, s1, -1
	s_add_i32 s50, 16, 0x10000
	s_cmp_eq_u32 s49, 12
	s_cselect_b32 s9, s3, s7
	s_cselect_b32 s8, s23, s6
	v_add_u32_e32 v151, s50, v176
	s_cselect_b32 s7, s21, s42
	s_cselect_b32 s6, s28, s29
	s_add_i32 s52, 16, 0x14000
	ds_read_b128 v[132:135], v151
	ds_read_b128 v[152:155], v151 offset:1024
	ds_read_b128 v[156:159], v151 offset:2048
	ds_read_b128 v[160:163], v151 offset:3072
	v_add_u32_e32 v151, s52, v176
	ds_read_b128 v[164:167], v151
	ds_read_b128 v[168:171], v151 offset:1024
	ds_read_b128 v[172:175], v151 offset:2048
	ds_read_b128 v[180:183], v151 offset:3072
	v_lshl_add_u64 v[216:217], s[0:1], 0, v[146:147]
	s_add_i32 m0, s37, 0xc000
	ds_read_b128 v[184:187], v178
	ds_read_b128 v[188:191], v178 offset:1024
	ds_read_b128 v[192:195], v178 offset:2048
	ds_read_b128 v[196:199], v178 offset:3072
	ds_read_b128 v[200:203], v178 offset:4096
	ds_read_b128 v[204:207], v178 offset:5120
	ds_read_b128 v[208:211], v178 offset:6144
	ds_read_b128 v[212:215], v178 offset:7168
	global_load_lds_dwordx4 v[216:217], off
	v_lshl_add_u64 v[216:217], s[0:1], 0, v[148:149]
	s_add_i32 m0, s37, 0xe000
	s_nop 0
	global_load_lds_dwordx4 v[216:217], off
	s_waitcnt vmcnt(8)
	s_waitcnt lgkmcnt(0)
	s_barrier
	s_setprio 1
	v_mfma_f32_16x16x32_bf16 v[128:131], v[132:135], v[184:187], v[128:131]
	v_mfma_f32_16x16x32_bf16 v[124:127], v[156:159], v[184:187], v[124:127]
	v_mfma_f32_16x16x32_bf16 v[112:115], v[132:135], v[192:195], v[112:115]
	v_mfma_f32_16x16x32_bf16 v[108:111], v[156:159], v[192:195], v[108:111]
	v_mfma_f32_16x16x32_bf16 v[96:99], v[132:135], v[200:203], v[96:99]
	v_mfma_f32_16x16x32_bf16 v[92:95], v[156:159], v[200:203], v[92:95]
	v_mfma_f32_16x16x32_bf16 v[80:83], v[132:135], v[208:211], v[80:83]
	v_mfma_f32_16x16x32_bf16 v[76:79], v[156:159], v[208:211], v[76:79]
	v_mfma_f32_16x16x32_bf16 v[128:131], v[152:155], v[188:191], v[128:131]
	v_mfma_f32_16x16x32_bf16 v[124:127], v[160:163], v[188:191], v[124:127]
	v_mfma_f32_16x16x32_bf16 v[112:115], v[152:155], v[196:199], v[112:115]
	v_mfma_f32_16x16x32_bf16 v[108:111], v[160:163], v[196:199], v[108:111]
	v_mfma_f32_16x16x32_bf16 v[96:99], v[152:155], v[204:207], v[96:99]
	v_mfma_f32_16x16x32_bf16 v[92:95], v[160:163], v[204:207], v[92:95]
	v_mfma_f32_16x16x32_bf16 v[80:83], v[152:155], v[212:215], v[80:83]
	v_mfma_f32_16x16x32_bf16 v[76:79], v[160:163], v[212:215], v[76:79]
	s_setprio 0
	s_setprio 1
	v_mfma_f32_16x16x32_bf16 v[120:123], v[164:167], v[184:187], v[120:123]
	v_mfma_f32_16x16x32_bf16 v[116:119], v[172:175], v[184:187], v[116:119]
	v_mfma_f32_16x16x32_bf16 v[104:107], v[164:167], v[192:195], v[104:107]
	v_mfma_f32_16x16x32_bf16 v[100:103], v[172:175], v[192:195], v[100:103]
	v_mfma_f32_16x16x32_bf16 v[88:91], v[164:167], v[200:203], v[88:91]
	v_mfma_f32_16x16x32_bf16 v[84:87], v[172:175], v[200:203], v[84:87]
	v_mfma_f32_16x16x32_bf16 v[72:75], v[164:167], v[208:211], v[72:75]
	v_mfma_f32_16x16x32_bf16 v[68:71], v[172:175], v[208:211], v[68:71]
	v_mfma_f32_16x16x32_bf16 v[120:123], v[168:171], v[188:191], v[120:123]
	v_mfma_f32_16x16x32_bf16 v[116:119], v[180:183], v[188:191], v[116:119]
	v_mfma_f32_16x16x32_bf16 v[104:107], v[168:171], v[196:199], v[104:107]
	v_mfma_f32_16x16x32_bf16 v[100:103], v[180:183], v[196:199], v[100:103]
	v_mfma_f32_16x16x32_bf16 v[88:91], v[168:171], v[204:207], v[88:91]
	v_mfma_f32_16x16x32_bf16 v[84:87], v[180:183], v[204:207], v[84:87]
	v_mfma_f32_16x16x32_bf16 v[72:75], v[168:171], v[212:215], v[72:75]
	v_mfma_f32_16x16x32_bf16 v[68:71], v[180:183], v[212:215], v[68:71]
	s_setprio 0
	s_barrier
	s_add_i32 s50, s50, s36
	v_lshl_add_u64 v[216:217], s[6:7], 0, v[138:139]
	s_mov_b32 m0, s50
	ds_read_b128 v[184:187], v178 offset:16384
	ds_read_b128 v[188:191], v178 offset:17408
	ds_read_b128 v[192:195], v178 offset:18432
	ds_read_b128 v[196:199], v178 offset:19456
	ds_read_b128 v[200:203], v178 offset:20480
	ds_read_b128 v[204:207], v178 offset:21504
	ds_read_b128 v[208:211], v178 offset:22528
	ds_read_b128 v[212:215], v178 offset:23552
	global_load_lds_dwordx4 v[216:217], off
	s_add_i32 m0, s50, 0x2000
	s_add_u32 s50, s6, 0x40000
	v_lshl_add_u64 v[218:219], s[6:7], 0, v[0:1]
	s_addc_u32 s51, s7, 0
	s_add_i32 s52, s52, s36
	global_load_lds_dwordx4 v[218:219], off
	v_lshl_add_u64 v[220:221], s[50:51], 0, v[138:139]
	s_mov_b32 m0, s52
	v_lshl_add_u64 v[224:225], s[8:9], 0, v[136:137]
	global_load_lds_dwordx4 v[220:221], off
	v_lshl_add_u64 v[220:221], s[50:51], 0, v[0:1]
	s_add_i32 m0, s52, 0x2000
	s_nop 0
	global_load_lds_dwordx4 v[220:221], off
	v_lshl_add_u64 v[220:221], s[8:9], 0, v[140:141]
	s_waitcnt vmcnt(6)
	s_waitcnt lgkmcnt(0)
	s_barrier
	s_setprio 1
	v_mfma_f32_16x16x32_bf16 v[64:67], v[132:135], v[184:187], v[64:67]
	v_mfma_f32_16x16x32_bf16 v[60:63], v[156:159], v[184:187], v[60:63]
	v_mfma_f32_16x16x32_bf16 v[48:51], v[132:135], v[192:195], v[48:51]
	v_mfma_f32_16x16x32_bf16 v[44:47], v[156:159], v[192:195], v[44:47]
	v_mfma_f32_16x16x32_bf16 v[32:35], v[132:135], v[200:203], v[32:35]
	v_mfma_f32_16x16x32_bf16 v[28:31], v[156:159], v[200:203], v[28:31]
	v_mfma_f32_16x16x32_bf16 v[16:19], v[132:135], v[208:211], v[16:19]
	v_mfma_f32_16x16x32_bf16 v[12:15], v[156:159], v[208:211], v[12:15]
	v_mfma_f32_16x16x32_bf16 v[64:67], v[152:155], v[188:191], v[64:67]
	v_mfma_f32_16x16x32_bf16 v[60:63], v[160:163], v[188:191], v[60:63]
	v_mfma_f32_16x16x32_bf16 v[48:51], v[152:155], v[196:199], v[48:51]
	v_mfma_f32_16x16x32_bf16 v[44:47], v[160:163], v[196:199], v[44:47]
	v_mfma_f32_16x16x32_bf16 v[32:35], v[152:155], v[204:207], v[32:35]
	v_mfma_f32_16x16x32_bf16 v[28:31], v[160:163], v[204:207], v[28:31]
	v_mfma_f32_16x16x32_bf16 v[16:19], v[152:155], v[212:215], v[16:19]
	v_mfma_f32_16x16x32_bf16 v[12:15], v[160:163], v[212:215], v[12:15]
	s_setprio 0
	s_setprio 1
	v_mfma_f32_16x16x32_bf16 v[56:59], v[164:167], v[184:187], v[56:59]
	v_mfma_f32_16x16x32_bf16 v[52:55], v[172:175], v[184:187], v[52:55]
	v_mfma_f32_16x16x32_bf16 v[40:43], v[164:167], v[192:195], v[40:43]
	v_mfma_f32_16x16x32_bf16 v[36:39], v[172:175], v[192:195], v[36:39]
	v_mfma_f32_16x16x32_bf16 v[24:27], v[164:167], v[200:203], v[24:27]
	v_mfma_f32_16x16x32_bf16 v[20:23], v[172:175], v[200:203], v[20:23]
	v_mfma_f32_16x16x32_bf16 v[8:11], v[164:167], v[208:211], v[8:11]
	v_mfma_f32_16x16x32_bf16 v[4:7], v[172:175], v[208:211], v[4:7]
	v_mfma_f32_16x16x32_bf16 v[56:59], v[168:171], v[188:191], v[56:59]
	v_mfma_f32_16x16x32_bf16 v[52:55], v[180:183], v[188:191], v[52:55]
	v_mfma_f32_16x16x32_bf16 v[40:43], v[168:171], v[196:199], v[40:43]
	v_mfma_f32_16x16x32_bf16 v[36:39], v[180:183], v[196:199], v[36:39]
	v_mfma_f32_16x16x32_bf16 v[24:27], v[168:171], v[204:207], v[24:27]
	v_mfma_f32_16x16x32_bf16 v[20:23], v[180:183], v[204:207], v[20:23]
	v_mfma_f32_16x16x32_bf16 v[8:11], v[168:171], v[212:215], v[8:11]
	v_mfma_f32_16x16x32_bf16 v[4:7], v[180:183], v[212:215], v[4:7]
	s_setprio 0
	s_barrier
.Lb1_ph3:
	s_add_i32 s50, 16, 0x18000
	v_add_u32_e32 v151, s50, v176
	s_add_i32 s51, 16, 0x1c000
	ds_read_b128 v[132:135], v151
	ds_read_b128 v[152:155], v151 offset:1024
	ds_read_b128 v[156:159], v151 offset:2048
	ds_read_b128 v[160:163], v151 offset:3072
	v_add_u32_e32 v151, s51, v176
	ds_read_b128 v[164:167], v151
	ds_read_b128 v[168:171], v151 offset:1024
	ds_read_b128 v[172:175], v151 offset:2048
	ds_read_b128 v[180:183], v151 offset:3072
	s_mov_b32 m0, s37
	s_nop 0
	global_load_lds_dwordx4 v[220:221], off
	s_mov_b32 m0, s38
	s_nop 0
	global_load_lds_dwordx4 v[224:225], off
	s_add_u32 s8, s8, 0x40000
	s_addc_u32 s9, s9, 0
	s_mov_b32 m0, s39
	v_lshl_add_u64 v[226:227], s[8:9], 0, v[140:141]
	ds_read_b128 v[184:187], v178 offset:32768
	ds_read_b128 v[188:191], v178 offset:33792
	ds_read_b128 v[192:195], v178 offset:34816
	ds_read_b128 v[196:199], v178 offset:35840
	ds_read_b128 v[200:203], v178 offset:36864
	ds_read_b128 v[204:207], v178 offset:37888
	ds_read_b128 v[208:211], v178 offset:38912
	ds_read_b128 v[212:215], v178 offset:39936
	global_load_lds_dwordx4 v[226:227], off
	v_lshl_add_u64 v[226:227], s[8:9], 0, v[136:137]
	s_mov_b32 m0, s40
	s_nop 0
	global_load_lds_dwordx4 v[226:227], off
	s_waitcnt vmcnt(8)
	s_waitcnt lgkmcnt(0)
	s_barrier
	s_setprio 1
	v_mfma_f32_16x16x32_bf16 v[128:131], v[132:135], v[184:187], v[128:131]
	v_mfma_f32_16x16x32_bf16 v[124:127], v[156:159], v[184:187], v[124:127]
	v_mfma_f32_16x16x32_bf16 v[112:115], v[132:135], v[192:195], v[112:115]
	v_mfma_f32_16x16x32_bf16 v[108:111], v[156:159], v[192:195], v[108:111]
	v_mfma_f32_16x16x32_bf16 v[96:99], v[132:135], v[200:203], v[96:99]
	v_mfma_f32_16x16x32_bf16 v[92:95], v[156:159], v[200:203], v[92:95]
	v_mfma_f32_16x16x32_bf16 v[80:83], v[132:135], v[208:211], v[80:83]
	v_mfma_f32_16x16x32_bf16 v[76:79], v[156:159], v[208:211], v[76:79]
	v_mfma_f32_16x16x32_bf16 v[128:131], v[152:155], v[188:191], v[128:131]
	v_mfma_f32_16x16x32_bf16 v[124:127], v[160:163], v[188:191], v[124:127]
	v_mfma_f32_16x16x32_bf16 v[112:115], v[152:155], v[196:199], v[112:115]
	v_mfma_f32_16x16x32_bf16 v[108:111], v[160:163], v[196:199], v[108:111]
	v_mfma_f32_16x16x32_bf16 v[96:99], v[152:155], v[204:207], v[96:99]
	v_mfma_f32_16x16x32_bf16 v[92:95], v[160:163], v[204:207], v[92:95]
	v_mfma_f32_16x16x32_bf16 v[80:83], v[152:155], v[212:215], v[80:83]
	v_mfma_f32_16x16x32_bf16 v[76:79], v[160:163], v[212:215], v[76:79]
	s_setprio 0
	s_setprio 1
	v_mfma_f32_16x16x32_bf16 v[120:123], v[164:167], v[184:187], v[120:123]
	v_mfma_f32_16x16x32_bf16 v[116:119], v[172:175], v[184:187], v[116:119]
	v_mfma_f32_16x16x32_bf16 v[104:107], v[164:167], v[192:195], v[104:107]
	v_mfma_f32_16x16x32_bf16 v[100:103], v[172:175], v[192:195], v[100:103]
	v_mfma_f32_16x16x32_bf16 v[88:91], v[164:167], v[200:203], v[88:91]
	v_mfma_f32_16x16x32_bf16 v[84:87], v[172:175], v[200:203], v[84:87]
	v_mfma_f32_16x16x32_bf16 v[72:75], v[164:167], v[208:211], v[72:75]
	v_mfma_f32_16x16x32_bf16 v[68:71], v[172:175], v[208:211], v[68:71]
	v_mfma_f32_16x16x32_bf16 v[120:123], v[168:171], v[188:191], v[120:123]
	v_mfma_f32_16x16x32_bf16 v[116:119], v[180:183], v[188:191], v[116:119]
	v_mfma_f32_16x16x32_bf16 v[104:107], v[168:171], v[196:199], v[104:107]
	v_mfma_f32_16x16x32_bf16 v[100:103], v[180:183], v[196:199], v[100:103]
	v_mfma_f32_16x16x32_bf16 v[88:91], v[168:171], v[204:207], v[88:91]
	v_mfma_f32_16x16x32_bf16 v[84:87], v[180:183], v[204:207], v[84:87]
	v_mfma_f32_16x16x32_bf16 v[72:75], v[168:171], v[212:215], v[72:75]
	v_mfma_f32_16x16x32_bf16 v[68:71], v[180:183], v[212:215], v[68:71]
	s_setprio 0
	s_barrier
	s_add_i32 s8, s50, s36
	v_lshl_add_u64 v[216:217], v[216:217], 0, s[84:85]
	s_mov_b32 m0, s8
	ds_read_b128 v[184:187], v178 offset:49152
	ds_read_b128 v[188:191], v178 offset:50176
	ds_read_b128 v[192:195], v178 offset:51200
	ds_read_b128 v[196:199], v178 offset:52224
	ds_read_b128 v[200:203], v178 offset:53248
	ds_read_b128 v[204:207], v178 offset:54272
	ds_read_b128 v[208:211], v178 offset:55296
	ds_read_b128 v[212:215], v178 offset:56320
	global_load_lds_dwordx4 v[216:217], off
	s_add_i32 m0, s8, 0x2000
	s_add_u32 s6, s6, 0x40080
	v_lshl_add_u64 v[216:217], v[218:219], 0, s[84:85]
	s_addc_u32 s7, s7, 0
	s_add_i32 s8, s51, s36
	global_load_lds_dwordx4 v[216:217], off
	v_lshl_add_u64 v[216:217], s[6:7], 0, v[138:139]
	s_mov_b32 m0, s8
	s_nop 0
	global_load_lds_dwordx4 v[216:217], off
	v_lshl_add_u64 v[216:217], s[6:7], 0, v[0:1]
	s_add_i32 m0, s8, 0x2000
	s_nop 0
	global_load_lds_dwordx4 v[216:217], off
	v_lshl_add_u64 v[216:217], v[220:221], 0, s[84:85]
	s_mov_b32 m0, s44
	s_nop 0
	global_load_lds_dwordx4 v[216:217], off
	v_lshl_add_u64 v[216:217], v[224:225], 0, s[84:85]
	s_mov_b32 m0, s45
	s_nop 0
	global_load_lds_dwordx4 v[216:217], off
	s_waitcnt vmcnt(8)
	s_waitcnt lgkmcnt(0)
	s_barrier
	s_setprio 1
	v_mfma_f32_16x16x32_bf16 v[64:67], v[132:135], v[184:187], v[64:67]
	v_mfma_f32_16x16x32_bf16 v[60:63], v[156:159], v[184:187], v[60:63]
	v_mfma_f32_16x16x32_bf16 v[48:51], v[132:135], v[192:195], v[48:51]
	v_mfma_f32_16x16x32_bf16 v[44:47], v[156:159], v[192:195], v[44:47]
	v_mfma_f32_16x16x32_bf16 v[32:35], v[132:135], v[200:203], v[32:35]
	v_mfma_f32_16x16x32_bf16 v[28:31], v[156:159], v[200:203], v[28:31]
	v_mfma_f32_16x16x32_bf16 v[16:19], v[132:135], v[208:211], v[16:19]
	v_mfma_f32_16x16x32_bf16 v[12:15], v[156:159], v[208:211], v[12:15]
	v_mfma_f32_16x16x32_bf16 v[64:67], v[152:155], v[188:191], v[64:67]
	v_mfma_f32_16x16x32_bf16 v[60:63], v[160:163], v[188:191], v[60:63]
	v_mfma_f32_16x16x32_bf16 v[48:51], v[152:155], v[196:199], v[48:51]
	v_mfma_f32_16x16x32_bf16 v[44:47], v[160:163], v[196:199], v[44:47]
	v_mfma_f32_16x16x32_bf16 v[32:35], v[152:155], v[204:207], v[32:35]
	v_mfma_f32_16x16x32_bf16 v[28:31], v[160:163], v[204:207], v[28:31]
	v_mfma_f32_16x16x32_bf16 v[16:19], v[152:155], v[212:215], v[16:19]
	v_mfma_f32_16x16x32_bf16 v[12:15], v[160:163], v[212:215], v[12:15]
	s_setprio 0
	s_setprio 1
	v_mfma_f32_16x16x32_bf16 v[56:59], v[164:167], v[184:187], v[56:59]
	v_mfma_f32_16x16x32_bf16 v[52:55], v[172:175], v[184:187], v[52:55]
	v_mfma_f32_16x16x32_bf16 v[40:43], v[164:167], v[192:195], v[40:43]
	v_mfma_f32_16x16x32_bf16 v[36:39], v[172:175], v[192:195], v[36:39]
	v_mfma_f32_16x16x32_bf16 v[24:27], v[164:167], v[200:203], v[24:27]
	v_mfma_f32_16x16x32_bf16 v[20:23], v[172:175], v[200:203], v[20:23]
	v_mfma_f32_16x16x32_bf16 v[8:11], v[164:167], v[208:211], v[8:11]
	v_mfma_f32_16x16x32_bf16 v[4:7], v[172:175], v[208:211], v[4:7]
	v_mfma_f32_16x16x32_bf16 v[56:59], v[168:171], v[188:191], v[56:59]
	v_mfma_f32_16x16x32_bf16 v[52:55], v[180:183], v[188:191], v[52:55]
	v_mfma_f32_16x16x32_bf16 v[40:43], v[168:171], v[196:199], v[40:43]
	v_mfma_f32_16x16x32_bf16 v[36:39], v[180:183], v[196:199], v[36:39]
	v_mfma_f32_16x16x32_bf16 v[24:27], v[168:171], v[204:207], v[24:27]
	v_mfma_f32_16x16x32_bf16 v[20:23], v[180:183], v[204:207], v[20:23]
	v_mfma_f32_16x16x32_bf16 v[8:11], v[168:171], v[212:215], v[8:11]
	v_mfma_f32_16x16x32_bf16 v[4:7], v[180:183], v[212:215], v[4:7]
	s_setprio 0
	s_barrier
	s_add_i32 s49, s49, 2
	s_add_u32 s0, s0, 0x100
	s_addc_u32 s1, s1, 0
	s_add_u32 s29, s29, 0x100
	s_addc_u32 s42, s42, 0
	s_cmp_gt_u32 s49, 13
	s_cbranch_scc0 .LBB0_156
	s_and_b64 vcc, exec, s[18:19]
	s_cbranch_vccz .LBB0_159
	s_barrier

.LBB0_445:
	s_ashr_i32 s23, s22, 31
	s_lshl_b64 s[24:25], s[22:23], 19
	s_add_u32 s24, s34, s24
	s_addc_u32 s25, s35, s25
	s_and_b64 s[26:27], s[6:7], exec
	s_cselect_b32 s3, s25, s1
	s_cselect_b32 s23, s24, s0
	s_ashr_i32 s21, s20, 31
	s_lshl_b64 s[26:27], s[20:21], 19
	s_add_u32 s26, s36, s26
	s_addc_u32 s27, s37, s27
	s_and_b64 s[30:31], s[6:7], exec
	s_cselect_b32 s21, s27, s29
	s_cselect_b32 s48, s26, s28
	s_add_u32 s0, s0, 0x40080
	s_addc_u32 s1, s1, 0
	s_add_u32 s49, s28, 0x100
	s_addc_u32 s50, s29, 0
	s_mov_b32 s51, -2
	s_waitcnt vmcnt(0)
	s_add_u32 s28, s0, 0xfffc0080
	s_addc_u32 s29, s1, -1
	s_add_i32 s52, 16, 0x10000
	s_cmp_eq_u32 s51, 12
	s_cselect_b32 s31, s3, s29
	s_cselect_b32 s30, s23, s28
	v_add_u32_e32 v3, s52, v175
	s_cselect_b32 s29, s21, s50
	s_cselect_b32 s28, s48, s49
	s_add_i32 s54, 16, 0x14000
	ds_read_b128 v[142:145], v3
	ds_read_b128 v[146:149], v3 offset:1024
	ds_read_b128 v[150:153], v3 offset:2048
	ds_read_b128 v[154:157], v3 offset:3072
	v_add_u32_e32 v3, s54, v175
	ds_read_b128 v[158:161], v3
	ds_read_b128 v[162:165], v3 offset:1024
	ds_read_b128 v[166:169], v3 offset:2048
	ds_read_b128 v[170:173], v3 offset:3072
	v_lshl_add_u64 v[210:211], s[0:1], 0, v[138:139]
	s_add_i32 m0, s39, 0xc000
	ds_read_b128 v[178:181], v177
	ds_read_b128 v[182:185], v177 offset:1024
	ds_read_b128 v[186:189], v177 offset:2048
	ds_read_b128 v[190:193], v177 offset:3072
	ds_read_b128 v[194:197], v177 offset:4096
	ds_read_b128 v[198:201], v177 offset:5120
	ds_read_b128 v[202:205], v177 offset:6144
	ds_read_b128 v[206:209], v177 offset:7168
	global_load_lds_dwordx4 v[210:211], off
	v_lshl_add_u64 v[210:211], s[0:1], 0, v[140:141]
	s_add_i32 m0, s39, 0xe000
	s_nop 0
	global_load_lds_dwordx4 v[210:211], off
	s_waitcnt vmcnt(8)
	s_waitcnt lgkmcnt(0)
	s_barrier
	s_setprio 1
	v_mfma_f32_16x16x32_bf16 v[128:131], v[142:145], v[178:181], 0
	v_mfma_f32_16x16x32_bf16 v[120:123], v[150:153], v[178:181], 0
	v_mfma_f32_16x16x32_bf16 v[112:115], v[142:145], v[186:189], 0
	v_mfma_f32_16x16x32_bf16 v[104:107], v[150:153], v[186:189], 0
	v_mfma_f32_16x16x32_bf16 v[96:99], v[142:145], v[194:197], 0
	v_mfma_f32_16x16x32_bf16 v[88:91], v[150:153], v[194:197], 0
	v_mfma_f32_16x16x32_bf16 v[80:83], v[142:145], v[202:205], 0
	v_mfma_f32_16x16x32_bf16 v[72:75], v[150:153], v[202:205], 0
	v_mfma_f32_16x16x32_bf16 v[128:131], v[146:149], v[182:185], v[128:131]
	v_mfma_f32_16x16x32_bf16 v[120:123], v[154:157], v[182:185], v[120:123]
	v_mfma_f32_16x16x32_bf16 v[112:115], v[146:149], v[190:193], v[112:115]
	v_mfma_f32_16x16x32_bf16 v[104:107], v[154:157], v[190:193], v[104:107]
	v_mfma_f32_16x16x32_bf16 v[96:99], v[146:149], v[198:201], v[96:99]
	v_mfma_f32_16x16x32_bf16 v[88:91], v[154:157], v[198:201], v[88:91]
	v_mfma_f32_16x16x32_bf16 v[80:83], v[146:149], v[206:209], v[80:83]
	v_mfma_f32_16x16x32_bf16 v[72:75], v[154:157], v[206:209], v[72:75]
	s_setprio 0
	s_setprio 1
	v_mfma_f32_16x16x32_bf16 v[124:127], v[158:161], v[178:181], 0
	v_mfma_f32_16x16x32_bf16 v[116:119], v[166:169], v[178:181], 0
	v_mfma_f32_16x16x32_bf16 v[108:111], v[158:161], v[186:189], 0
	v_mfma_f32_16x16x32_bf16 v[100:103], v[166:169], v[186:189], 0
	v_mfma_f32_16x16x32_bf16 v[92:95], v[158:161], v[194:197], 0
	v_mfma_f32_16x16x32_bf16 v[84:87], v[166:169], v[194:197], 0
	v_mfma_f32_16x16x32_bf16 v[76:79], v[158:161], v[202:205], 0
	v_mfma_f32_16x16x32_bf16 v[68:71], v[166:169], v[202:205], 0
	v_mfma_f32_16x16x32_bf16 v[124:127], v[162:165], v[182:185], v[124:127]
	v_mfma_f32_16x16x32_bf16 v[116:119], v[170:173], v[182:185], v[116:119]
	v_mfma_f32_16x16x32_bf16 v[108:111], v[162:165], v[190:193], v[108:111]
	v_mfma_f32_16x16x32_bf16 v[100:103], v[170:173], v[190:193], v[100:103]
	v_mfma_f32_16x16x32_bf16 v[92:95], v[162:165], v[198:201], v[92:95]
	v_mfma_f32_16x16x32_bf16 v[84:87], v[170:173], v[198:201], v[84:87]
	v_mfma_f32_16x16x32_bf16 v[76:79], v[162:165], v[206:209], v[76:79]
	v_mfma_f32_16x16x32_bf16 v[68:71], v[170:173], v[206:209], v[68:71]
	s_setprio 0
	s_barrier
	s_add_i32 s52, s52, s38
	v_lshl_add_u64 v[210:211], s[28:29], 0, v[134:135]
	s_mov_b32 m0, s52
	ds_read_b128 v[178:181], v177 offset:16384
	ds_read_b128 v[182:185], v177 offset:17408
	ds_read_b128 v[186:189], v177 offset:18432
	ds_read_b128 v[190:193], v177 offset:19456
	ds_read_b128 v[194:197], v177 offset:20480
	ds_read_b128 v[198:201], v177 offset:21504
	ds_read_b128 v[202:205], v177 offset:22528
	ds_read_b128 v[206:209], v177 offset:23552
	global_load_lds_dwordx4 v[210:211], off
	s_add_i32 m0, s52, 0x2000
	s_add_u32 s52, s28, 0x40000
	v_lshl_add_u64 v[212:213], s[28:29], 0, v[0:1]
	s_addc_u32 s53, s29, 0
	s_add_i32 s54, s54, s38
	global_load_lds_dwordx4 v[212:213], off
	v_lshl_add_u64 v[214:215], s[52:53], 0, v[134:135]
	s_mov_b32 m0, s54
	v_lshl_add_u64 v[216:217], s[30:31], 0, v[132:133]
	global_load_lds_dwordx4 v[214:215], off
	v_lshl_add_u64 v[214:215], s[52:53], 0, v[0:1]
	s_add_i32 m0, s54, 0x2000
	s_nop 0
	global_load_lds_dwordx4 v[214:215], off
	v_lshl_add_u64 v[214:215], s[30:31], 0, v[136:137]
	s_waitcnt vmcnt(6)
	s_waitcnt lgkmcnt(0)
	s_barrier
	s_setprio 1
	v_mfma_f32_16x16x32_bf16 v[64:67], v[142:145], v[178:181], 0
	v_mfma_f32_16x16x32_bf16 v[56:59], v[150:153], v[178:181], 0
	v_mfma_f32_16x16x32_bf16 v[48:51], v[142:145], v[186:189], 0
	v_mfma_f32_16x16x32_bf16 v[40:43], v[150:153], v[186:189], 0
	v_mfma_f32_16x16x32_bf16 v[32:35], v[142:145], v[194:197], 0
	v_mfma_f32_16x16x32_bf16 v[24:27], v[150:153], v[194:197], 0
	v_mfma_f32_16x16x32_bf16 v[16:19], v[142:145], v[202:205], 0
	v_mfma_f32_16x16x32_bf16 v[8:11], v[150:153], v[202:205], 0
	v_mfma_f32_16x16x32_bf16 v[64:67], v[146:149], v[182:185], v[64:67]
	v_mfma_f32_16x16x32_bf16 v[56:59], v[154:157], v[182:185], v[56:59]
	v_mfma_f32_16x16x32_bf16 v[48:51], v[146:149], v[190:193], v[48:51]
	v_mfma_f32_16x16x32_bf16 v[40:43], v[154:157], v[190:193], v[40:43]
	v_mfma_f32_16x16x32_bf16 v[32:35], v[146:149], v[198:201], v[32:35]
	v_mfma_f32_16x16x32_bf16 v[24:27], v[154:157], v[198:201], v[24:27]
	v_mfma_f32_16x16x32_bf16 v[16:19], v[146:149], v[206:209], v[16:19]
	v_mfma_f32_16x16x32_bf16 v[8:11], v[154:157], v[206:209], v[8:11]
	s_setprio 0
	s_setprio 1
	v_mfma_f32_16x16x32_bf16 v[60:63], v[158:161], v[178:181], 0
	v_mfma_f32_16x16x32_bf16 v[52:55], v[166:169], v[178:181], 0
	v_mfma_f32_16x16x32_bf16 v[44:47], v[158:161], v[186:189], 0
	v_mfma_f32_16x16x32_bf16 v[36:39], v[166:169], v[186:189], 0
	v_mfma_f32_16x16x32_bf16 v[28:31], v[158:161], v[194:197], 0
	v_mfma_f32_16x16x32_bf16 v[20:23], v[166:169], v[194:197], 0
	v_mfma_f32_16x16x32_bf16 v[12:15], v[158:161], v[202:205], 0
	v_mfma_f32_16x16x32_bf16 v[4:7], v[166:169], v[202:205], 0
	v_mfma_f32_16x16x32_bf16 v[60:63], v[162:165], v[182:185], v[60:63]
	v_mfma_f32_16x16x32_bf16 v[52:55], v[170:173], v[182:185], v[52:55]
	v_mfma_f32_16x16x32_bf16 v[44:47], v[162:165], v[190:193], v[44:47]
	v_mfma_f32_16x16x32_bf16 v[36:39], v[170:173], v[190:193], v[36:39]
	v_mfma_f32_16x16x32_bf16 v[28:31], v[162:165], v[198:201], v[28:31]
	v_mfma_f32_16x16x32_bf16 v[20:23], v[170:173], v[198:201], v[20:23]
	v_mfma_f32_16x16x32_bf16 v[12:15], v[162:165], v[206:209], v[12:15]
	v_mfma_f32_16x16x32_bf16 v[4:7], v[170:173], v[206:209], v[4:7]
	s_setprio 0
	s_barrier
	s_branch .La1_ph3
.LBB0_446:
	s_add_u32 s28, s0, 0xfffc0080
	s_addc_u32 s29, s1, -1
	s_add_i32 s52, 16, 0x10000
	s_cmp_eq_u32 s51, 12
	s_cselect_b32 s31, s3, s29
	s_cselect_b32 s30, s23, s28
	v_add_u32_e32 v3, s52, v175
	s_cselect_b32 s29, s21, s50
	s_cselect_b32 s28, s48, s49
	s_add_i32 s54, 16, 0x14000
	ds_read_b128 v[142:145], v3
	ds_read_b128 v[146:149], v3 offset:1024
	ds_read_b128 v[150:153], v3 offset:2048
	ds_read_b128 v[154:157], v3 offset:3072
	v_add_u32_e32 v3, s54, v175
	ds_read_b128 v[158:161], v3
	ds_read_b128 v[162:165], v3 offset:1024
	ds_read_b128 v[166:169], v3 offset:2048
	ds_read_b128 v[170:173], v3 offset:3072
	v_lshl_add_u64 v[210:211], s[0:1], 0, v[138:139]
	s_add_i32 m0, s39, 0xc000
	ds_read_b128 v[178:181], v177
	ds_read_b128 v[182:185], v177 offset:1024
	ds_read_b128 v[186:189], v177 offset:2048
	ds_read_b128 v[190:193], v177 offset:3072
	ds_read_b128 v[194:197], v177 offset:4096
	ds_read_b128 v[198:201], v177 offset:5120
	ds_read_b128 v[202:205], v177 offset:6144
	ds_read_b128 v[206:209], v177 offset:7168
	global_load_lds_dwordx4 v[210:211], off
	v_lshl_add_u64 v[210:211], s[0:1], 0, v[140:141]
	s_add_i32 m0, s39, 0xe000
	s_nop 0
	global_load_lds_dwordx4 v[210:211], off
	s_waitcnt vmcnt(8)
	s_waitcnt lgkmcnt(0)
	s_barrier
	s_setprio 1
	v_mfma_f32_16x16x32_bf16 v[128:131], v[142:145], v[178:181], v[128:131]
	v_mfma_f32_16x16x32_bf16 v[120:123], v[150:153], v[178:181], v[120:123]
	v_mfma_f32_16x16x32_bf16 v[112:115], v[142:145], v[186:189], v[112:115]
	v_mfma_f32_16x16x32_bf16 v[104:107], v[150:153], v[186:189], v[104:107]
	v_mfma_f32_16x16x32_bf16 v[96:99], v[142:145], v[194:197], v[96:99]
	v_mfma_f32_16x16x32_bf16 v[88:91], v[150:153], v[194:197], v[88:91]
	v_mfma_f32_16x16x32_bf16 v[80:83], v[142:145], v[202:205], v[80:83]
	v_mfma_f32_16x16x32_bf16 v[72:75], v[150:153], v[202:205], v[72:75]
	v_mfma_f32_16x16x32_bf16 v[128:131], v[146:149], v[182:185], v[128:131]
	v_mfma_f32_16x16x32_bf16 v[120:123], v[154:157], v[182:185], v[120:123]
	v_mfma_f32_16x16x32_bf16 v[112:115], v[146:149], v[190:193], v[112:115]
	v_mfma_f32_16x16x32_bf16 v[104:107], v[154:157], v[190:193], v[104:107]
	v_mfma_f32_16x16x32_bf16 v[96:99], v[146:149], v[198:201], v[96:99]
	v_mfma_f32_16x16x32_bf16 v[88:91], v[154:157], v[198:201], v[88:91]
	v_mfma_f32_16x16x32_bf16 v[80:83], v[146:149], v[206:209], v[80:83]
	v_mfma_f32_16x16x32_bf16 v[72:75], v[154:157], v[206:209], v[72:75]
	s_setprio 0
	s_setprio 1
	v_mfma_f32_16x16x32_bf16 v[124:127], v[158:161], v[178:181], v[124:127]
	v_mfma_f32_16x16x32_bf16 v[116:119], v[166:169], v[178:181], v[116:119]
	v_mfma_f32_16x16x32_bf16 v[108:111], v[158:161], v[186:189], v[108:111]
	v_mfma_f32_16x16x32_bf16 v[100:103], v[166:169], v[186:189], v[100:103]
	v_mfma_f32_16x16x32_bf16 v[92:95], v[158:161], v[194:197], v[92:95]
	v_mfma_f32_16x16x32_bf16 v[84:87], v[166:169], v[194:197], v[84:87]
	v_mfma_f32_16x16x32_bf16 v[76:79], v[158:161], v[202:205], v[76:79]
	v_mfma_f32_16x16x32_bf16 v[68:71], v[166:169], v[202:205], v[68:71]
	v_mfma_f32_16x16x32_bf16 v[124:127], v[162:165], v[182:185], v[124:127]
	v_mfma_f32_16x16x32_bf16 v[116:119], v[170:173], v[182:185], v[116:119]
	v_mfma_f32_16x16x32_bf16 v[108:111], v[162:165], v[190:193], v[108:111]
	v_mfma_f32_16x16x32_bf16 v[100:103], v[170:173], v[190:193], v[100:103]
	v_mfma_f32_16x16x32_bf16 v[92:95], v[162:165], v[198:201], v[92:95]
	v_mfma_f32_16x16x32_bf16 v[84:87], v[170:173], v[198:201], v[84:87]
	v_mfma_f32_16x16x32_bf16 v[76:79], v[162:165], v[206:209], v[76:79]
	v_mfma_f32_16x16x32_bf16 v[68:71], v[170:173], v[206:209], v[68:71]
	s_setprio 0
	s_barrier
	s_add_i32 s52, s52, s38
	v_lshl_add_u64 v[210:211], s[28:29], 0, v[134:135]
	s_mov_b32 m0, s52
	ds_read_b128 v[178:181], v177 offset:16384
	ds_read_b128 v[182:185], v177 offset:17408
	ds_read_b128 v[186:189], v177 offset:18432
	ds_read_b128 v[190:193], v177 offset:19456
	ds_read_b128 v[194:197], v177 offset:20480
	ds_read_b128 v[198:201], v177 offset:21504
	ds_read_b128 v[202:205], v177 offset:22528
	ds_read_b128 v[206:209], v177 offset:23552
	global_load_lds_dwordx4 v[210:211], off
	s_add_i32 m0, s52, 0x2000
	s_add_u32 s52, s28, 0x40000
	v_lshl_add_u64 v[212:213], s[28:29], 0, v[0:1]
	s_addc_u32 s53, s29, 0
	s_add_i32 s54, s54, s38
	global_load_lds_dwordx4 v[212:213], off
	v_lshl_add_u64 v[214:215], s[52:53], 0, v[134:135]
	s_mov_b32 m0, s54
	v_lshl_add_u64 v[216:217], s[30:31], 0, v[132:133]
	global_load_lds_dwordx4 v[214:215], off
	v_lshl_add_u64 v[214:215], s[52:53], 0, v[0:1]
	s_add_i32 m0, s54, 0x2000
	s_nop 0
	global_load_lds_dwordx4 v[214:215], off
	v_lshl_add_u64 v[214:215], s[30:31], 0, v[136:137]
	s_waitcnt vmcnt(6)
	s_waitcnt lgkmcnt(0)
	s_barrier
	s_setprio 1
	v_mfma_f32_16x16x32_bf16 v[64:67], v[142:145], v[178:181], v[64:67]
	v_mfma_f32_16x16x32_bf16 v[56:59], v[150:153], v[178:181], v[56:59]
	v_mfma_f32_16x16x32_bf16 v[48:51], v[142:145], v[186:189], v[48:51]
	v_mfma_f32_16x16x32_bf16 v[40:43], v[150:153], v[186:189], v[40:43]
	v_mfma_f32_16x16x32_bf16 v[32:35], v[142:145], v[194:197], v[32:35]
	v_mfma_f32_16x16x32_bf16 v[24:27], v[150:153], v[194:197], v[24:27]
	v_mfma_f32_16x16x32_bf16 v[16:19], v[142:145], v[202:205], v[16:19]
	v_mfma_f32_16x16x32_bf16 v[8:11], v[150:153], v[202:205], v[8:11]
	v_mfma_f32_16x16x32_bf16 v[64:67], v[146:149], v[182:185], v[64:67]
	v_mfma_f32_16x16x32_bf16 v[56:59], v[154:157], v[182:185], v[56:59]
	v_mfma_f32_16x16x32_bf16 v[48:51], v[146:149], v[190:193], v[48:51]
	v_mfma_f32_16x16x32_bf16 v[40:43], v[154:157], v[190:193], v[40:43]
	v_mfma_f32_16x16x32_bf16 v[32:35], v[146:149], v[198:201], v[32:35]
	v_mfma_f32_16x16x32_bf16 v[24:27], v[154:157], v[198:201], v[24:27]
	v_mfma_f32_16x16x32_bf16 v[16:19], v[146:149], v[206:209], v[16:19]
	v_mfma_f32_16x16x32_bf16 v[8:11], v[154:157], v[206:209], v[8:11]
	s_setprio 0
	s_setprio 1
	v_mfma_f32_16x16x32_bf16 v[60:63], v[158:161], v[178:181], v[60:63]
	v_mfma_f32_16x16x32_bf16 v[52:55], v[166:169], v[178:181], v[52:55]
	v_mfma_f32_16x16x32_bf16 v[44:47], v[158:161], v[186:189], v[44:47]
	v_mfma_f32_16x16x32_bf16 v[36:39], v[166:169], v[186:189], v[36:39]
	v_mfma_f32_16x16x32_bf16 v[28:31], v[158:161], v[194:197], v[28:31]
	v_mfma_f32_16x16x32_bf16 v[20:23], v[166:169], v[194:197], v[20:23]
	v_mfma_f32_16x16x32_bf16 v[12:15], v[158:161], v[202:205], v[12:15]
	v_mfma_f32_16x16x32_bf16 v[4:7], v[166:169], v[202:205], v[4:7]
	v_mfma_f32_16x16x32_bf16 v[60:63], v[162:165], v[182:185], v[60:63]
	v_mfma_f32_16x16x32_bf16 v[52:55], v[170:173], v[182:185], v[52:55]
	v_mfma_f32_16x16x32_bf16 v[44:47], v[162:165], v[190:193], v[44:47]
	v_mfma_f32_16x16x32_bf16 v[36:39], v[170:173], v[190:193], v[36:39]
	v_mfma_f32_16x16x32_bf16 v[28:31], v[162:165], v[198:201], v[28:31]
	v_mfma_f32_16x16x32_bf16 v[20:23], v[170:173], v[198:201], v[20:23]
	v_mfma_f32_16x16x32_bf16 v[12:15], v[162:165], v[206:209], v[12:15]
	v_mfma_f32_16x16x32_bf16 v[4:7], v[170:173], v[206:209], v[4:7]
	s_setprio 0
	s_barrier
.La1_ph3:
	s_add_i32 s52, 16, 0x18000
	v_add_u32_e32 v3, s52, v175
	s_add_i32 s53, 16, 0x1c000
	ds_read_b128 v[142:145], v3
	ds_read_b128 v[146:149], v3 offset:1024
	ds_read_b128 v[150:153], v3 offset:2048
	ds_read_b128 v[154:157], v3 offset:3072
	v_add_u32_e32 v3, s53, v175
	ds_read_b128 v[158:161], v3
	ds_read_b128 v[162:165], v3 offset:1024
	ds_read_b128 v[166:169], v3 offset:2048
	ds_read_b128 v[170:173], v3 offset:3072
	s_mov_b32 m0, s39
	s_nop 0
	global_load_lds_dwordx4 v[214:215], off
	s_mov_b32 m0, s40
	s_nop 0
	global_load_lds_dwordx4 v[216:217], off
	s_add_u32 s30, s30, 0x40000
	s_addc_u32 s31, s31, 0
	s_mov_b32 m0, s41
	v_lshl_add_u64 v[218:219], s[30:31], 0, v[136:137]
	ds_read_b128 v[178:181], v177 offset:32768
	ds_read_b128 v[182:185], v177 offset:33792
	ds_read_b128 v[186:189], v177 offset:34816
	ds_read_b128 v[190:193], v177 offset:35840
	ds_read_b128 v[194:197], v177 offset:36864
	ds_read_b128 v[198:201], v177 offset:37888
	ds_read_b128 v[202:205], v177 offset:38912
	ds_read_b128 v[206:209], v177 offset:39936
	global_load_lds_dwordx4 v[218:219], off
	v_lshl_add_u64 v[218:219], s[30:31], 0, v[132:133]
	s_mov_b32 m0, s42
	s_nop 0
	global_load_lds_dwordx4 v[218:219], off
	s_waitcnt vmcnt(8)
	s_waitcnt lgkmcnt(0)
	s_barrier
	s_setprio 1
	v_mfma_f32_16x16x32_bf16 v[128:131], v[142:145], v[178:181], v[128:131]
	v_mfma_f32_16x16x32_bf16 v[120:123], v[150:153], v[178:181], v[120:123]
	v_mfma_f32_16x16x32_bf16 v[112:115], v[142:145], v[186:189], v[112:115]
	v_mfma_f32_16x16x32_bf16 v[104:107], v[150:153], v[186:189], v[104:107]
	v_mfma_f32_16x16x32_bf16 v[96:99], v[142:145], v[194:197], v[96:99]
	v_mfma_f32_16x16x32_bf16 v[88:91], v[150:153], v[194:197], v[88:91]
	v_mfma_f32_16x16x32_bf16 v[80:83], v[142:145], v[202:205], v[80:83]
	v_mfma_f32_16x16x32_bf16 v[72:75], v[150:153], v[202:205], v[72:75]
	v_mfma_f32_16x16x32_bf16 v[128:131], v[146:149], v[182:185], v[128:131]
	v_mfma_f32_16x16x32_bf16 v[120:123], v[154:157], v[182:185], v[120:123]
	v_mfma_f32_16x16x32_bf16 v[112:115], v[146:149], v[190:193], v[112:115]
	v_mfma_f32_16x16x32_bf16 v[104:107], v[154:157], v[190:193], v[104:107]
	v_mfma_f32_16x16x32_bf16 v[96:99], v[146:149], v[198:201], v[96:99]
	v_mfma_f32_16x16x32_bf16 v[88:91], v[154:157], v[198:201], v[88:91]
	v_mfma_f32_16x16x32_bf16 v[80:83], v[146:149], v[206:209], v[80:83]
	v_mfma_f32_16x16x32_bf16 v[72:75], v[154:157], v[206:209], v[72:75]
	s_setprio 0
	s_setprio 1
	v_mfma_f32_16x16x32_bf16 v[124:127], v[158:161], v[178:181], v[124:127]
	v_mfma_f32_16x16x32_bf16 v[116:119], v[166:169], v[178:181], v[116:119]
	v_mfma_f32_16x16x32_bf16 v[108:111], v[158:161], v[186:189], v[108:111]
	v_mfma_f32_16x16x32_bf16 v[100:103], v[166:169], v[186:189], v[100:103]
	v_mfma_f32_16x16x32_bf16 v[92:95], v[158:161], v[194:197], v[92:95]
	v_mfma_f32_16x16x32_bf16 v[84:87], v[166:169], v[194:197], v[84:87]
	v_mfma_f32_16x16x32_bf16 v[76:79], v[158:161], v[202:205], v[76:79]
	v_mfma_f32_16x16x32_bf16 v[68:71], v[166:169], v[202:205], v[68:71]
	v_mfma_f32_16x16x32_bf16 v[124:127], v[162:165], v[182:185], v[124:127]
	v_mfma_f32_16x16x32_bf16 v[116:119], v[170:173], v[182:185], v[116:119]
	v_mfma_f32_16x16x32_bf16 v[108:111], v[162:165], v[190:193], v[108:111]
	v_mfma_f32_16x16x32_bf16 v[100:103], v[170:173], v[190:193], v[100:103]
	v_mfma_f32_16x16x32_bf16 v[92:95], v[162:165], v[198:201], v[92:95]
	v_mfma_f32_16x16x32_bf16 v[84:87], v[170:173], v[198:201], v[84:87]
	v_mfma_f32_16x16x32_bf16 v[76:79], v[162:165], v[206:209], v[76:79]
	v_mfma_f32_16x16x32_bf16 v[68:71], v[170:173], v[206:209], v[68:71]
	s_setprio 0
	s_barrier
	s_add_i32 s30, s52, s38
	v_lshl_add_u64 v[210:211], v[210:211], 0, s[84:85]
	s_mov_b32 m0, s30
	ds_read_b128 v[178:181], v177 offset:49152
	ds_read_b128 v[182:185], v177 offset:50176
	ds_read_b128 v[186:189], v177 offset:51200
	ds_read_b128 v[190:193], v177 offset:52224
	ds_read_b128 v[194:197], v177 offset:53248
	ds_read_b128 v[198:201], v177 offset:54272
	ds_read_b128 v[202:205], v177 offset:55296
	ds_read_b128 v[206:209], v177 offset:56320
	global_load_lds_dwordx4 v[210:211], off
	s_add_i32 m0, s30, 0x2000
	s_add_u32 s28, s28, 0x40080
	v_lshl_add_u64 v[210:211], v[212:213], 0, s[84:85]
	s_addc_u32 s29, s29, 0
	s_add_i32 s30, s53, s38
	global_load_lds_dwordx4 v[210:211], off
	v_lshl_add_u64 v[210:211], s[28:29], 0, v[134:135]
	s_mov_b32 m0, s30
	s_nop 0
	global_load_lds_dwordx4 v[210:211], off
	v_lshl_add_u64 v[210:211], s[28:29], 0, v[0:1]
	s_add_i32 m0, s30, 0x2000
	s_nop 0
	global_load_lds_dwordx4 v[210:211], off
	v_lshl_add_u64 v[210:211], v[214:215], 0, s[84:85]
	s_mov_b32 m0, s44
	s_nop 0
	global_load_lds_dwordx4 v[210:211], off
	v_lshl_add_u64 v[210:211], v[216:217], 0, s[84:85]
	s_mov_b32 m0, s45
	s_nop 0
	global_load_lds_dwordx4 v[210:211], off
	s_waitcnt vmcnt(8)
	s_waitcnt lgkmcnt(0)
	s_barrier
	s_setprio 1
	v_mfma_f32_16x16x32_bf16 v[64:67], v[142:145], v[178:181], v[64:67]
	v_mfma_f32_16x16x32_bf16 v[56:59], v[150:153], v[178:181], v[56:59]
	v_mfma_f32_16x16x32_bf16 v[48:51], v[142:145], v[186:189], v[48:51]
	v_mfma_f32_16x16x32_bf16 v[40:43], v[150:153], v[186:189], v[40:43]
	v_mfma_f32_16x16x32_bf16 v[32:35], v[142:145], v[194:197], v[32:35]
	v_mfma_f32_16x16x32_bf16 v[24:27], v[150:153], v[194:197], v[24:27]
	v_mfma_f32_16x16x32_bf16 v[16:19], v[142:145], v[202:205], v[16:19]
	v_mfma_f32_16x16x32_bf16 v[8:11], v[150:153], v[202:205], v[8:11]
	v_mfma_f32_16x16x32_bf16 v[64:67], v[146:149], v[182:185], v[64:67]
	v_mfma_f32_16x16x32_bf16 v[56:59], v[154:157], v[182:185], v[56:59]
	v_mfma_f32_16x16x32_bf16 v[48:51], v[146:149], v[190:193], v[48:51]
	v_mfma_f32_16x16x32_bf16 v[40:43], v[154:157], v[190:193], v[40:43]
	v_mfma_f32_16x16x32_bf16 v[32:35], v[146:149], v[198:201], v[32:35]
	v_mfma_f32_16x16x32_bf16 v[24:27], v[154:157], v[198:201], v[24:27]
	v_mfma_f32_16x16x32_bf16 v[16:19], v[146:149], v[206:209], v[16:19]
	v_mfma_f32_16x16x32_bf16 v[8:11], v[154:157], v[206:209], v[8:11]
	s_setprio 0
	s_setprio 1
	v_mfma_f32_16x16x32_bf16 v[60:63], v[158:161], v[178:181], v[60:63]
	v_mfma_f32_16x16x32_bf16 v[52:55], v[166:169], v[178:181], v[52:55]
	v_mfma_f32_16x16x32_bf16 v[44:47], v[158:161], v[186:189], v[44:47]
	v_mfma_f32_16x16x32_bf16 v[36:39], v[166:169], v[186:189], v[36:39]
	v_mfma_f32_16x16x32_bf16 v[28:31], v[158:161], v[194:197], v[28:31]
	v_mfma_f32_16x16x32_bf16 v[20:23], v[166:169], v[194:197], v[20:23]
	v_mfma_f32_16x16x32_bf16 v[12:15], v[158:161], v[202:205], v[12:15]
	v_mfma_f32_16x16x32_bf16 v[4:7], v[166:169], v[202:205], v[4:7]
	v_mfma_f32_16x16x32_bf16 v[60:63], v[162:165], v[182:185], v[60:63]
	v_mfma_f32_16x16x32_bf16 v[52:55], v[170:173], v[182:185], v[52:55]
	v_mfma_f32_16x16x32_bf16 v[44:47], v[162:165], v[190:193], v[44:47]
	v_mfma_f32_16x16x32_bf16 v[36:39], v[170:173], v[190:193], v[36:39]
	v_mfma_f32_16x16x32_bf16 v[28:31], v[162:165], v[198:201], v[28:31]
	v_mfma_f32_16x16x32_bf16 v[20:23], v[170:173], v[198:201], v[20:23]
	v_mfma_f32_16x16x32_bf16 v[12:15], v[162:165], v[206:209], v[12:15]
	v_mfma_f32_16x16x32_bf16 v[4:7], v[170:173], v[206:209], v[4:7]
	s_setprio 0
	s_barrier
	s_add_i32 s51, s51, 2
	s_add_u32 s0, s0, 0x100
	s_addc_u32 s1, s1, 0
	s_add_u32 s49, s49, 0x100
	s_addc_u32 s50, s50, 0
	s_cmp_gt_u32 s51, 13
	s_cbranch_scc0 .LBB0_446
	s_and_b64 vcc, exec, s[18:19]
	s_cbranch_vccz .LBB0_449
	s_barrier

.LBB0_620:
	s_add_i32 s58, s34, 2
	s_add_u32 s59, s22, s30
	s_addc_u32 s35, s23, s31
	s_add_u32 s60, s0, s30
	s_addc_u32 s61, s1, s31
	s_add_i32 s62, 16, 0x10000
	s_cmp_eq_u32 s54, s34
	s_cselect_b32 s35, s9, s35
	s_cselect_b32 s34, s8, s59
	v_add_u32_e32 v149, s62, v147
	s_cselect_b32 s61, s29, s61
	s_cselect_b32 s60, s28, s60
	s_add_i32 s59, 16, 0x14000
	ds_read_b128 v[150:153], v149
	ds_read_b128 v[154:157], v149 offset:1024
	ds_read_b128 v[158:161], v149 offset:2048
	ds_read_b128 v[162:165], v149 offset:3072
	v_add_u32_e32 v149, s59, v147
	ds_read_b128 v[166:169], v149
	ds_read_b128 v[170:173], v149 offset:1024
	ds_read_b128 v[174:177], v149 offset:2048
	ds_read_b128 v[178:181], v149 offset:3072
	v_lshl_add_u64 v[214:215], s[22:23], 0, v[144:145]
	s_add_i32 m0, s47, 0xc000
	ds_read_b128 v[182:185], v148
	ds_read_b128 v[186:189], v148 offset:1024
	ds_read_b128 v[190:193], v148 offset:2048
	ds_read_b128 v[194:197], v148 offset:3072
	ds_read_b128 v[198:201], v148 offset:4096
	ds_read_b128 v[202:205], v148 offset:5120
	ds_read_b128 v[206:209], v148 offset:6144
	ds_read_b128 v[210:213], v148 offset:7168
	global_load_lds_dwordx4 v[214:215], off
	v_lshl_add_u64 v[214:215], s[22:23], 0, v[142:143]
	s_add_i32 m0, s47, 0xe000
	s_nop 0
	global_load_lds_dwordx4 v[214:215], off
	s_waitcnt vmcnt(8)
	s_waitcnt lgkmcnt(0)
	s_barrier
	s_setprio 1
	v_mfma_f32_16x16x32_bf16 v[128:131], v[150:153], v[182:185], v[128:131]
	v_mfma_f32_16x16x32_bf16 v[124:127], v[158:161], v[182:185], v[124:127]
	v_mfma_f32_16x16x32_bf16 v[120:123], v[150:153], v[190:193], v[120:123]
	v_mfma_f32_16x16x32_bf16 v[116:119], v[158:161], v[190:193], v[116:119]
	v_mfma_f32_16x16x32_bf16 v[112:115], v[150:153], v[198:201], v[112:115]
	v_mfma_f32_16x16x32_bf16 v[108:111], v[158:161], v[198:201], v[108:111]
	v_mfma_f32_16x16x32_bf16 v[104:107], v[150:153], v[206:209], v[104:107]
	v_mfma_f32_16x16x32_bf16 v[100:103], v[158:161], v[206:209], v[100:103]
	v_mfma_f32_16x16x32_bf16 v[128:131], v[154:157], v[186:189], v[128:131]
	v_mfma_f32_16x16x32_bf16 v[124:127], v[162:165], v[186:189], v[124:127]
	v_mfma_f32_16x16x32_bf16 v[120:123], v[154:157], v[194:197], v[120:123]
	v_mfma_f32_16x16x32_bf16 v[116:119], v[162:165], v[194:197], v[116:119]
	v_mfma_f32_16x16x32_bf16 v[112:115], v[154:157], v[202:205], v[112:115]
	v_mfma_f32_16x16x32_bf16 v[108:111], v[162:165], v[202:205], v[108:111]
	v_mfma_f32_16x16x32_bf16 v[104:107], v[154:157], v[210:213], v[104:107]
	v_mfma_f32_16x16x32_bf16 v[100:103], v[162:165], v[210:213], v[100:103]
	s_setprio 0
	s_setprio 1
	v_mfma_f32_16x16x32_bf16 v[64:67], v[166:169], v[182:185], v[64:67]
	v_mfma_f32_16x16x32_bf16 v[60:63], v[174:177], v[182:185], v[60:63]
	v_mfma_f32_16x16x32_bf16 v[56:59], v[166:169], v[190:193], v[56:59]
	v_mfma_f32_16x16x32_bf16 v[52:55], v[174:177], v[190:193], v[52:55]
	v_mfma_f32_16x16x32_bf16 v[48:51], v[166:169], v[198:201], v[48:51]
	v_mfma_f32_16x16x32_bf16 v[44:47], v[174:177], v[198:201], v[44:47]
	v_mfma_f32_16x16x32_bf16 v[40:43], v[166:169], v[206:209], v[40:43]
	v_mfma_f32_16x16x32_bf16 v[36:39], v[174:177], v[206:209], v[36:39]
	v_mfma_f32_16x16x32_bf16 v[64:67], v[170:173], v[186:189], v[64:67]
	v_mfma_f32_16x16x32_bf16 v[60:63], v[178:181], v[186:189], v[60:63]
	v_mfma_f32_16x16x32_bf16 v[56:59], v[170:173], v[194:197], v[56:59]
	v_mfma_f32_16x16x32_bf16 v[52:55], v[178:181], v[194:197], v[52:55]
	v_mfma_f32_16x16x32_bf16 v[48:51], v[170:173], v[202:205], v[48:51]
	v_mfma_f32_16x16x32_bf16 v[44:47], v[178:181], v[202:205], v[44:47]
	v_mfma_f32_16x16x32_bf16 v[40:43], v[170:173], v[210:213], v[40:43]
	v_mfma_f32_16x16x32_bf16 v[36:39], v[178:181], v[210:213], v[36:39]
	s_setprio 0
	s_barrier
	s_add_i32 s62, s62, s42
	v_lshl_add_u64 v[214:215], s[60:61], 0, v[134:135]
	s_mov_b32 m0, s62
	ds_read_b128 v[182:185], v148 offset:16384
	ds_read_b128 v[186:189], v148 offset:17408
	ds_read_b128 v[190:193], v148 offset:18432
	ds_read_b128 v[194:197], v148 offset:19456
	ds_read_b128 v[198:201], v148 offset:20480
	ds_read_b128 v[202:205], v148 offset:21504
	ds_read_b128 v[206:209], v148 offset:22528
	ds_read_b128 v[210:213], v148 offset:23552
	global_load_lds_dwordx4 v[214:215], off
	s_add_i32 m0, s62, 0x2000
	v_lshl_add_u64 v[216:217], s[60:61], 0, v[0:1]
	s_add_u32 s60, s60, s40
	s_addc_u32 s61, s61, 0
	s_add_i32 s59, s59, s42
	global_load_lds_dwordx4 v[216:217], off
	v_lshl_add_u64 v[218:219], s[60:61], 0, v[134:135]
	s_mov_b32 m0, s59
	v_lshl_add_u64 v[220:221], s[60:61], 0, v[0:1]
	global_load_lds_dwordx4 v[218:219], off
	s_add_i32 m0, s59, 0x2000
	v_lshl_add_u64 v[224:225], s[34:35], 0, v[136:137]
	global_load_lds_dwordx4 v[220:221], off
	v_lshl_add_u64 v[226:227], s[34:35], 0, v[132:133]
	s_waitcnt vmcnt(6)
	s_waitcnt lgkmcnt(0)
	s_barrier
	s_setprio 1
	v_mfma_f32_16x16x32_bf16 v[96:99], v[150:153], v[182:185], v[96:99]
	v_mfma_f32_16x16x32_bf16 v[92:95], v[158:161], v[182:185], v[92:95]
	v_mfma_f32_16x16x32_bf16 v[88:91], v[150:153], v[190:193], v[88:91]
	v_mfma_f32_16x16x32_bf16 v[84:87], v[158:161], v[190:193], v[84:87]
	v_mfma_f32_16x16x32_bf16 v[80:83], v[150:153], v[198:201], v[80:83]
	v_mfma_f32_16x16x32_bf16 v[76:79], v[158:161], v[198:201], v[76:79]
	v_mfma_f32_16x16x32_bf16 v[72:75], v[150:153], v[206:209], v[72:75]
	v_mfma_f32_16x16x32_bf16 v[68:71], v[158:161], v[206:209], v[68:71]
	v_mfma_f32_16x16x32_bf16 v[96:99], v[154:157], v[186:189], v[96:99]
	v_mfma_f32_16x16x32_bf16 v[92:95], v[162:165], v[186:189], v[92:95]
	v_mfma_f32_16x16x32_bf16 v[88:91], v[154:157], v[194:197], v[88:91]
	v_mfma_f32_16x16x32_bf16 v[84:87], v[162:165], v[194:197], v[84:87]
	v_mfma_f32_16x16x32_bf16 v[80:83], v[154:157], v[202:205], v[80:83]
	v_mfma_f32_16x16x32_bf16 v[76:79], v[162:165], v[202:205], v[76:79]
	v_mfma_f32_16x16x32_bf16 v[72:75], v[154:157], v[210:213], v[72:75]
	v_mfma_f32_16x16x32_bf16 v[68:71], v[162:165], v[210:213], v[68:71]
	s_setprio 0
	s_setprio 1
	v_mfma_f32_16x16x32_bf16 v[32:35], v[166:169], v[182:185], v[32:35]
	v_mfma_f32_16x16x32_bf16 v[28:31], v[174:177], v[182:185], v[28:31]
	v_mfma_f32_16x16x32_bf16 v[24:27], v[166:169], v[190:193], v[24:27]
	v_mfma_f32_16x16x32_bf16 v[20:23], v[174:177], v[190:193], v[20:23]
	v_mfma_f32_16x16x32_bf16 v[16:19], v[166:169], v[198:201], v[16:19]
	v_mfma_f32_16x16x32_bf16 v[12:15], v[174:177], v[198:201], v[12:15]
	v_mfma_f32_16x16x32_bf16 v[8:11], v[166:169], v[206:209], v[8:11]
	v_mfma_f32_16x16x32_bf16 v[4:7], v[174:177], v[206:209], v[4:7]
	v_mfma_f32_16x16x32_bf16 v[32:35], v[170:173], v[186:189], v[32:35]
	v_mfma_f32_16x16x32_bf16 v[28:31], v[178:181], v[186:189], v[28:31]
	v_mfma_f32_16x16x32_bf16 v[24:27], v[170:173], v[194:197], v[24:27]
	v_mfma_f32_16x16x32_bf16 v[20:23], v[178:181], v[194:197], v[20:23]
	v_mfma_f32_16x16x32_bf16 v[16:19], v[170:173], v[202:205], v[16:19]
	v_mfma_f32_16x16x32_bf16 v[12:15], v[178:181], v[202:205], v[12:15]
	v_mfma_f32_16x16x32_bf16 v[8:11], v[170:173], v[210:213], v[8:11]
	v_mfma_f32_16x16x32_bf16 v[4:7], v[178:181], v[210:213], v[4:7]
	s_setprio 0
	s_barrier
	s_add_i32 s59, 16, 0x18000
	v_add_u32_e32 v149, s59, v147
	s_add_i32 s60, 16, 0x1c000
	ds_read_b128 v[150:153], v149
	ds_read_b128 v[154:157], v149 offset:1024
	ds_read_b128 v[158:161], v149 offset:2048
	ds_read_b128 v[162:165], v149 offset:3072
	v_add_u32_e32 v149, s60, v147
	ds_read_b128 v[166:169], v149
	ds_read_b128 v[170:173], v149 offset:1024
	ds_read_b128 v[174:177], v149 offset:2048
	ds_read_b128 v[178:181], v149 offset:3072
	s_mov_b32 m0, s47
	s_nop 0
	global_load_lds_dwordx4 v[224:225], off
	s_mov_b32 m0, s48
	s_nop 0
	global_load_lds_dwordx4 v[226:227], off
	s_add_u32 s34, s34, s40
	s_addc_u32 s35, s35, 0
	s_mov_b32 m0, s49
	v_lshl_add_u64 v[228:229], s[34:35], 0, v[136:137]
	ds_read_b128 v[182:185], v148 offset:32768
	ds_read_b128 v[186:189], v148 offset:33792
	ds_read_b128 v[190:193], v148 offset:34816
	ds_read_b128 v[194:197], v148 offset:35840
	ds_read_b128 v[198:201], v148 offset:36864
	ds_read_b128 v[202:205], v148 offset:37888
	ds_read_b128 v[206:209], v148 offset:38912
	ds_read_b128 v[210:213], v148 offset:39936
	global_load_lds_dwordx4 v[228:229], off
	v_lshl_add_u64 v[228:229], s[34:35], 0, v[132:133]
	s_mov_b32 m0, s50
	s_nop 0
	global_load_lds_dwordx4 v[228:229], off
	s_waitcnt vmcnt(8)
	s_waitcnt lgkmcnt(0)
	s_barrier
	s_setprio 1
	v_mfma_f32_16x16x32_bf16 v[128:131], v[150:153], v[182:185], v[128:131]
	v_mfma_f32_16x16x32_bf16 v[124:127], v[158:161], v[182:185], v[124:127]
	v_mfma_f32_16x16x32_bf16 v[120:123], v[150:153], v[190:193], v[120:123]
	v_mfma_f32_16x16x32_bf16 v[116:119], v[158:161], v[190:193], v[116:119]
	v_mfma_f32_16x16x32_bf16 v[112:115], v[150:153], v[198:201], v[112:115]
	v_mfma_f32_16x16x32_bf16 v[108:111], v[158:161], v[198:201], v[108:111]
	v_mfma_f32_16x16x32_bf16 v[104:107], v[150:153], v[206:209], v[104:107]
	v_mfma_f32_16x16x32_bf16 v[100:103], v[158:161], v[206:209], v[100:103]
	v_mfma_f32_16x16x32_bf16 v[128:131], v[154:157], v[186:189], v[128:131]
	v_mfma_f32_16x16x32_bf16 v[124:127], v[162:165], v[186:189], v[124:127]
	v_mfma_f32_16x16x32_bf16 v[120:123], v[154:157], v[194:197], v[120:123]
	v_mfma_f32_16x16x32_bf16 v[116:119], v[162:165], v[194:197], v[116:119]
	v_mfma_f32_16x16x32_bf16 v[112:115], v[154:157], v[202:205], v[112:115]
	v_mfma_f32_16x16x32_bf16 v[108:111], v[162:165], v[202:205], v[108:111]
	v_mfma_f32_16x16x32_bf16 v[104:107], v[154:157], v[210:213], v[104:107]
	v_mfma_f32_16x16x32_bf16 v[100:103], v[162:165], v[210:213], v[100:103]
	s_setprio 0
	s_setprio 1
	v_mfma_f32_16x16x32_bf16 v[64:67], v[166:169], v[182:185], v[64:67]
	v_mfma_f32_16x16x32_bf16 v[60:63], v[174:177], v[182:185], v[60:63]
	v_mfma_f32_16x16x32_bf16 v[56:59], v[166:169], v[190:193], v[56:59]
	v_mfma_f32_16x16x32_bf16 v[52:55], v[174:177], v[190:193], v[52:55]
	v_mfma_f32_16x16x32_bf16 v[48:51], v[166:169], v[198:201], v[48:51]
	v_mfma_f32_16x16x32_bf16 v[44:47], v[174:177], v[198:201], v[44:47]
	v_mfma_f32_16x16x32_bf16 v[40:43], v[166:169], v[206:209], v[40:43]
	v_mfma_f32_16x16x32_bf16 v[36:39], v[174:177], v[206:209], v[36:39]
	v_mfma_f32_16x16x32_bf16 v[64:67], v[170:173], v[186:189], v[64:67]
	v_mfma_f32_16x16x32_bf16 v[60:63], v[178:181], v[186:189], v[60:63]
	v_mfma_f32_16x16x32_bf16 v[56:59], v[170:173], v[194:197], v[56:59]
	v_mfma_f32_16x16x32_bf16 v[52:55], v[178:181], v[194:197], v[52:55]
	v_mfma_f32_16x16x32_bf16 v[48:51], v[170:173], v[202:205], v[48:51]
	v_mfma_f32_16x16x32_bf16 v[44:47], v[178:181], v[202:205], v[44:47]
	v_mfma_f32_16x16x32_bf16 v[40:43], v[170:173], v[210:213], v[40:43]
	v_mfma_f32_16x16x32_bf16 v[36:39], v[178:181], v[210:213], v[36:39]
	s_setprio 0
	s_barrier
	s_add_i32 s34, s59, s42
	v_lshl_add_u64 v[214:215], v[214:215], 0, s[84:85]
	s_mov_b32 m0, s34
	ds_read_b128 v[182:185], v148 offset:49152
	ds_read_b128 v[186:189], v148 offset:50176
	ds_read_b128 v[190:193], v148 offset:51200
	ds_read_b128 v[194:197], v148 offset:52224
	ds_read_b128 v[198:201], v148 offset:53248
	ds_read_b128 v[202:205], v148 offset:54272
	ds_read_b128 v[206:209], v148 offset:55296
	ds_read_b128 v[210:213], v148 offset:56320
	global_load_lds_dwordx4 v[214:215], off
	v_lshl_add_u64 v[214:215], v[216:217], 0, s[84:85]
	s_add_i32 m0, s34, 0x2000
	s_add_i32 s34, s60, s42
	global_load_lds_dwordx4 v[214:215], off
	v_lshl_add_u64 v[214:215], v[218:219], 0, s[84:85]
	s_mov_b32 m0, s34
	s_nop 0
	global_load_lds_dwordx4 v[214:215], off
	v_lshl_add_u64 v[214:215], v[220:221], 0, s[84:85]
	s_add_i32 m0, s34, 0x2000
	s_nop 0
	global_load_lds_dwordx4 v[214:215], off
	v_lshl_add_u64 v[214:215], v[224:225], 0, s[84:85]
	s_mov_b32 m0, s52
	s_nop 0
	global_load_lds_dwordx4 v[214:215], off
	v_lshl_add_u64 v[214:215], v[226:227], 0, s[84:85]
	s_mov_b32 m0, s53
	s_nop 0
	global_load_lds_dwordx4 v[214:215], off
	s_waitcnt vmcnt(8)
	s_waitcnt lgkmcnt(0)
	s_barrier
	s_setprio 1
	v_mfma_f32_16x16x32_bf16 v[96:99], v[150:153], v[182:185], v[96:99]
	v_mfma_f32_16x16x32_bf16 v[92:95], v[158:161], v[182:185], v[92:95]
	v_mfma_f32_16x16x32_bf16 v[88:91], v[150:153], v[190:193], v[88:91]
	v_mfma_f32_16x16x32_bf16 v[84:87], v[158:161], v[190:193], v[84:87]
	v_mfma_f32_16x16x32_bf16 v[80:83], v[150:153], v[198:201], v[80:83]
	v_mfma_f32_16x16x32_bf16 v[76:79], v[158:161], v[198:201], v[76:79]
	v_mfma_f32_16x16x32_bf16 v[72:75], v[150:153], v[206:209], v[72:75]
	v_mfma_f32_16x16x32_bf16 v[68:71], v[158:161], v[206:209], v[68:71]
	v_mfma_f32_16x16x32_bf16 v[96:99], v[154:157], v[186:189], v[96:99]
	v_mfma_f32_16x16x32_bf16 v[92:95], v[162:165], v[186:189], v[92:95]
	v_mfma_f32_16x16x32_bf16 v[88:91], v[154:157], v[194:197], v[88:91]
	v_mfma_f32_16x16x32_bf16 v[84:87], v[162:165], v[194:197], v[84:87]
	v_mfma_f32_16x16x32_bf16 v[80:83], v[154:157], v[202:205], v[80:83]
	v_mfma_f32_16x16x32_bf16 v[76:79], v[162:165], v[202:205], v[76:79]
	v_mfma_f32_16x16x32_bf16 v[72:75], v[154:157], v[210:213], v[72:75]
	v_mfma_f32_16x16x32_bf16 v[68:71], v[162:165], v[210:213], v[68:71]
	s_setprio 0
	s_setprio 1
	v_mfma_f32_16x16x32_bf16 v[32:35], v[166:169], v[182:185], v[32:35]
	v_mfma_f32_16x16x32_bf16 v[28:31], v[174:177], v[182:185], v[28:31]
	v_mfma_f32_16x16x32_bf16 v[24:27], v[166:169], v[190:193], v[24:27]
	v_mfma_f32_16x16x32_bf16 v[20:23], v[174:177], v[190:193], v[20:23]
	v_mfma_f32_16x16x32_bf16 v[16:19], v[166:169], v[198:201], v[16:19]
	v_mfma_f32_16x16x32_bf16 v[12:15], v[174:177], v[198:201], v[12:15]
	v_mfma_f32_16x16x32_bf16 v[8:11], v[166:169], v[206:209], v[8:11]
	v_mfma_f32_16x16x32_bf16 v[4:7], v[174:177], v[206:209], v[4:7]
	v_mfma_f32_16x16x32_bf16 v[32:35], v[170:173], v[186:189], v[32:35]
	v_mfma_f32_16x16x32_bf16 v[28:31], v[178:181], v[186:189], v[28:31]
	v_mfma_f32_16x16x32_bf16 v[24:27], v[170:173], v[194:197], v[24:27]
	v_mfma_f32_16x16x32_bf16 v[20:23], v[178:181], v[194:197], v[20:23]
	v_mfma_f32_16x16x32_bf16 v[16:19], v[170:173], v[202:205], v[16:19]
	v_mfma_f32_16x16x32_bf16 v[12:15], v[178:181], v[202:205], v[12:15]
	v_mfma_f32_16x16x32_bf16 v[8:11], v[170:173], v[210:213], v[8:11]
	v_mfma_f32_16x16x32_bf16 v[4:7], v[178:181], v[210:213], v[4:7]
	s_setprio 0
	s_barrier
	s_add_u32 s30, s30, 0x100
	s_addc_u32 s31, s31, 0
	v_lshl_add_u64 v[144:145], v[144:145], 0, s[86:87]
	v_lshl_add_u64 v[142:143], v[142:143], 0, s[86:87]
	s_cmp_ge_u32 s58, s51
	s_mov_b32 s34, s58
	s_cbranch_scc0 .LBB0_620
	s_and_b64 vcc, exec, s[26:27]
	s_cbranch_vccnz .LBB0_623
	s_and_b64 vcc, exec, s[6:7]
	s_cbranch_vccnz .LBB0_608
	s_branch .LBB0_624
